# plus P0 S5 KD-table reduction loop unrolled 16x with all 32 coefficient loads issued up front
# speedup vs baseline: 1.0060x; 1.0011x over previous
.LBB0_150:
	s_or_b64 exec, exec, s[28:29]
	s_cmp_lt_i32 s59, 64
	s_cselect_b64 s[8:9], -1, 0
	s_and_b64 s[10:11], s[8:9], s[4:5]
	s_waitcnt lgkmcnt(0)
	s_barrier
	s_and_saveexec_b64 s[8:9], s[10:11]
	s_cbranch_execz .LBB0_125
	v_lshl_or_b32 v14, s24, 10, v28
	v_ashrrev_i32_e32 v15, 31, v14
	v_lshlrev_b64 v[16:17], 2, v[14:15]
	v_lshl_add_u64 v[14:15], s[68:69], 0, v[16:17]
	v_lshl_add_u64 v[16:17], s[70:71], 0, v[16:17]
	v_mov_b32_e32 v2, 0
	s_mov_b32 s12, 0
	s_mov_b64 s[10:11], 0
	v_mov_b32_e32 v18, v31
	global_load_dwordx4 v[90:93], v[16:17], off offset:0
	global_load_dwordx4 v[94:97], v[14:15], off offset:0
	global_load_dwordx4 v[98:101], v[16:17], off offset:16
	global_load_dwordx4 v[102:105], v[14:15], off offset:16
	global_load_dwordx4 v[106:109], v[16:17], off offset:32
	global_load_dwordx4 v[110:113], v[14:15], off offset:32
	global_load_dwordx4 v[114:117], v[16:17], off offset:48
	global_load_dwordx4 v[118:121], v[14:15], off offset:48
	global_load_dwordx4 v[122:125], v[16:17], off offset:64
	global_load_dwordx4 v[126:129], v[14:15], off offset:64
	global_load_dwordx4 v[130:133], v[16:17], off offset:80
	global_load_dwordx4 v[134:137], v[14:15], off offset:80
	global_load_dwordx4 v[142:145], v[16:17], off offset:96
	global_load_dwordx4 v[146:149], v[14:15], off offset:96
	global_load_dwordx4 v[150:153], v[16:17], off offset:112
	global_load_dwordx4 v[154:157], v[14:15], off offset:112
	global_load_dwordx4 v[158:161], v[16:17], off offset:128
	global_load_dwordx4 v[162:165], v[14:15], off offset:128
	global_load_dwordx4 v[166:169], v[16:17], off offset:144
	global_load_dwordx4 v[170:173], v[14:15], off offset:144
	global_load_dwordx4 v[174:177], v[16:17], off offset:160
	global_load_dwordx4 v[182:185], v[14:15], off offset:160
	global_load_dwordx4 v[186:189], v[16:17], off offset:176
	global_load_dwordx4 v[190:193], v[14:15], off offset:176
	global_load_dwordx4 v[194:197], v[16:17], off offset:192
	global_load_dwordx4 v[198:201], v[14:15], off offset:192
	global_load_dwordx4 v[202:205], v[16:17], off offset:208
	global_load_dwordx4 v[206:209], v[14:15], off offset:208
	global_load_dwordx4 v[210:213], v[16:17], off offset:224
	global_load_dwordx4 v[214:217], v[14:15], off offset:224
	global_load_dwordx4 v[218:221], v[16:17], off offset:240
	global_load_dwordx4 v[222:225], v[14:15], off offset:240
	s_nop 0
	s_nop 0
	s_nop 0
	v_mov_b32_e32 v19, s12
	ds_read2_b64 v[42:45], v18 offset1:16
	ds_read2_b64 v[46:49], v18 offset0:32 offset1:48
	ds_read_b128 v[50:53], v19
	ds_read_b128 v[54:57], v19 offset:16
	s_add_i32 s12, s12, 32
	v_add_u32_e32 v18, 0x200, v18
	s_waitcnt vmcnt(31) lgkmcnt(1)
	v_pk_mul_f32 v[24:25], v[90:91], v[50:51] op_sel:[0,1] op_sel_hi:[0,0]
	s_waitcnt vmcnt(30)
	v_mov_b32_e32 v58, v95
	v_pk_mul_f32 v[20:21], v[90:91], v[52:53] op_sel:[1,1] op_sel_hi:[1,0]
	v_pk_fma_f32 v[66:67], v[94:95], v[50:51], v[24:25] neg_lo:[0,0,1] neg_hi:[0,0,1]
	v_pk_fma_f32 v[24:25], v[94:95], v[50:51], v[24:25] op_sel_hi:[0,1,1]
	s_waitcnt lgkmcnt(0)
	v_pk_mul_f32 v[60:61], v[92:93], v[54:55] op_sel:[0,1] op_sel_hi:[0,0]
	v_mov_b32_e32 v64, v93
	v_pk_fma_f32 v[50:51], v[58:59], v[52:53], v[20:21] neg_lo:[0,0,1] neg_hi:[0,0,1]
	v_pk_fma_f32 v[20:21], v[94:95], v[52:53], v[20:21] op_sel:[1,0,0]
	v_mov_b32_e32 v67, v25
	v_mov_b32_e32 v22, v97
	v_mov_b32_e32 v62, v97
	v_pk_fma_f32 v[38:39], v[96:97], v[54:55], v[60:61] neg_lo:[0,0,1] neg_hi:[0,0,1]
	v_pk_fma_f32 v[40:41], v[96:97], v[54:55], v[60:61] op_sel_hi:[0,1,1]
	v_pk_mul_f32 v[52:53], v[64:65], v[56:57] op_sel:[0,1] op_sel_hi:[0,0]
	v_mov_b32_e32 v51, v21
	v_pk_mul_f32 v[24:25], v[42:43], v[66:67]
	v_mov_b32_e32 v39, v41
	v_mov_b32_e32 v23, v93
	v_pk_fma_f32 v[20:21], v[22:23], v[56:57], v[52:53] neg_lo:[0,0,1] neg_hi:[0,0,1]
	v_pk_fma_f32 v[22:23], v[62:63], v[56:57], v[52:53] op_sel_hi:[0,1,1]
	v_pk_mul_f32 v[40:41], v[44:45], v[50:51]
	v_sub_f32_e32 v19, v24, v25
	v_pk_mul_f32 v[38:39], v[46:47], v[38:39]
	v_mov_b32_e32 v21, v23
	v_sub_f32_e32 v22, v40, v41
	v_add_f32_e32 v2, v2, v19
	v_sub_f32_e32 v23, v38, v39
	v_pk_mul_f32 v[20:21], v[48:49], v[20:21]
	v_add_f32_e32 v2, v2, v22
	v_sub_f32_e32 v19, v20, v21
	v_add_f32_e32 v2, v2, v23
	v_add_f32_e32 v2, v2, v19
	s_nop 0
	s_nop 0
	s_nop 0
	v_mov_b32_e32 v19, s12
	ds_read2_b64 v[42:45], v18 offset1:16
	ds_read2_b64 v[46:49], v18 offset0:32 offset1:48
	ds_read_b128 v[50:53], v19
	ds_read_b128 v[54:57], v19 offset:16
	s_add_i32 s12, s12, 32
	v_add_u32_e32 v18, 0x200, v18
	s_waitcnt vmcnt(29) lgkmcnt(1)
	v_pk_mul_f32 v[24:25], v[98:99], v[50:51] op_sel:[0,1] op_sel_hi:[0,0]
	s_waitcnt vmcnt(28)
	v_mov_b32_e32 v58, v103
	v_pk_mul_f32 v[20:21], v[98:99], v[52:53] op_sel:[1,1] op_sel_hi:[1,0]
	v_pk_fma_f32 v[66:67], v[102:103], v[50:51], v[24:25] neg_lo:[0,0,1] neg_hi:[0,0,1]
	v_pk_fma_f32 v[24:25], v[102:103], v[50:51], v[24:25] op_sel_hi:[0,1,1]
	s_waitcnt lgkmcnt(0)
	v_pk_mul_f32 v[60:61], v[100:101], v[54:55] op_sel:[0,1] op_sel_hi:[0,0]
	v_mov_b32_e32 v64, v101
	v_pk_fma_f32 v[50:51], v[58:59], v[52:53], v[20:21] neg_lo:[0,0,1] neg_hi:[0,0,1]
	v_pk_fma_f32 v[20:21], v[102:103], v[52:53], v[20:21] op_sel:[1,0,0]
	v_mov_b32_e32 v67, v25
	v_mov_b32_e32 v22, v105
	v_mov_b32_e32 v62, v105
	v_pk_fma_f32 v[38:39], v[104:105], v[54:55], v[60:61] neg_lo:[0,0,1] neg_hi:[0,0,1]
	v_pk_fma_f32 v[40:41], v[104:105], v[54:55], v[60:61] op_sel_hi:[0,1,1]
	v_pk_mul_f32 v[52:53], v[64:65], v[56:57] op_sel:[0,1] op_sel_hi:[0,0]
	v_mov_b32_e32 v51, v21
	v_pk_mul_f32 v[24:25], v[42:43], v[66:67]
	v_mov_b32_e32 v39, v41
	v_mov_b32_e32 v23, v101
	v_pk_fma_f32 v[20:21], v[22:23], v[56:57], v[52:53] neg_lo:[0,0,1] neg_hi:[0,0,1]
	v_pk_fma_f32 v[22:23], v[62:63], v[56:57], v[52:53] op_sel_hi:[0,1,1]
	v_pk_mul_f32 v[40:41], v[44:45], v[50:51]
	v_sub_f32_e32 v19, v24, v25
	v_pk_mul_f32 v[38:39], v[46:47], v[38:39]
	v_mov_b32_e32 v21, v23
	v_sub_f32_e32 v22, v40, v41
	v_add_f32_e32 v2, v2, v19
	v_sub_f32_e32 v23, v38, v39
	v_pk_mul_f32 v[20:21], v[48:49], v[20:21]
	v_add_f32_e32 v2, v2, v22
	v_sub_f32_e32 v19, v20, v21
	v_add_f32_e32 v2, v2, v23
	v_add_f32_e32 v2, v2, v19
	s_nop 0
	s_nop 0
	s_nop 0
	v_mov_b32_e32 v19, s12
	ds_read2_b64 v[42:45], v18 offset1:16
	ds_read2_b64 v[46:49], v18 offset0:32 offset1:48
	ds_read_b128 v[50:53], v19
	ds_read_b128 v[54:57], v19 offset:16
	s_add_i32 s12, s12, 32
	v_add_u32_e32 v18, 0x200, v18
	s_waitcnt vmcnt(27) lgkmcnt(1)
	v_pk_mul_f32 v[24:25], v[106:107], v[50:51] op_sel:[0,1] op_sel_hi:[0,0]
	s_waitcnt vmcnt(26)
	v_mov_b32_e32 v58, v111
	v_pk_mul_f32 v[20:21], v[106:107], v[52:53] op_sel:[1,1] op_sel_hi:[1,0]
	v_pk_fma_f32 v[66:67], v[110:111], v[50:51], v[24:25] neg_lo:[0,0,1] neg_hi:[0,0,1]
	v_pk_fma_f32 v[24:25], v[110:111], v[50:51], v[24:25] op_sel_hi:[0,1,1]
	s_waitcnt lgkmcnt(0)
	v_pk_mul_f32 v[60:61], v[108:109], v[54:55] op_sel:[0,1] op_sel_hi:[0,0]
	v_mov_b32_e32 v64, v109
	v_pk_fma_f32 v[50:51], v[58:59], v[52:53], v[20:21] neg_lo:[0,0,1] neg_hi:[0,0,1]
	v_pk_fma_f32 v[20:21], v[110:111], v[52:53], v[20:21] op_sel:[1,0,0]
	v_mov_b32_e32 v67, v25
	v_mov_b32_e32 v22, v113
	v_mov_b32_e32 v62, v113
	v_pk_fma_f32 v[38:39], v[112:113], v[54:55], v[60:61] neg_lo:[0,0,1] neg_hi:[0,0,1]
	v_pk_fma_f32 v[40:41], v[112:113], v[54:55], v[60:61] op_sel_hi:[0,1,1]
	v_pk_mul_f32 v[52:53], v[64:65], v[56:57] op_sel:[0,1] op_sel_hi:[0,0]
	v_mov_b32_e32 v51, v21
	v_pk_mul_f32 v[24:25], v[42:43], v[66:67]
	v_mov_b32_e32 v39, v41
	v_mov_b32_e32 v23, v109
	v_pk_fma_f32 v[20:21], v[22:23], v[56:57], v[52:53] neg_lo:[0,0,1] neg_hi:[0,0,1]
	v_pk_fma_f32 v[22:23], v[62:63], v[56:57], v[52:53] op_sel_hi:[0,1,1]
	v_pk_mul_f32 v[40:41], v[44:45], v[50:51]
	v_sub_f32_e32 v19, v24, v25
	v_pk_mul_f32 v[38:39], v[46:47], v[38:39]
	v_mov_b32_e32 v21, v23
	v_sub_f32_e32 v22, v40, v41
	v_add_f32_e32 v2, v2, v19
	v_sub_f32_e32 v23, v38, v39
	v_pk_mul_f32 v[20:21], v[48:49], v[20:21]
	v_add_f32_e32 v2, v2, v22
	v_sub_f32_e32 v19, v20, v21
	v_add_f32_e32 v2, v2, v23
	v_add_f32_e32 v2, v2, v19
	s_nop 0
	s_nop 0
	s_nop 0
	v_mov_b32_e32 v19, s12
	ds_read2_b64 v[42:45], v18 offset1:16
	ds_read2_b64 v[46:49], v18 offset0:32 offset1:48
	ds_read_b128 v[50:53], v19
	ds_read_b128 v[54:57], v19 offset:16
	s_add_i32 s12, s12, 32
	v_add_u32_e32 v18, 0x200, v18
	s_waitcnt vmcnt(25) lgkmcnt(1)
	v_pk_mul_f32 v[24:25], v[114:115], v[50:51] op_sel:[0,1] op_sel_hi:[0,0]
	s_waitcnt vmcnt(24)
	v_mov_b32_e32 v58, v119
	v_pk_mul_f32 v[20:21], v[114:115], v[52:53] op_sel:[1,1] op_sel_hi:[1,0]
	v_pk_fma_f32 v[66:67], v[118:119], v[50:51], v[24:25] neg_lo:[0,0,1] neg_hi:[0,0,1]
	v_pk_fma_f32 v[24:25], v[118:119], v[50:51], v[24:25] op_sel_hi:[0,1,1]
	s_waitcnt lgkmcnt(0)
	v_pk_mul_f32 v[60:61], v[116:117], v[54:55] op_sel:[0,1] op_sel_hi:[0,0]
	v_mov_b32_e32 v64, v117
	v_pk_fma_f32 v[50:51], v[58:59], v[52:53], v[20:21] neg_lo:[0,0,1] neg_hi:[0,0,1]
	v_pk_fma_f32 v[20:21], v[118:119], v[52:53], v[20:21] op_sel:[1,0,0]
	v_mov_b32_e32 v67, v25
	v_mov_b32_e32 v22, v121
	v_mov_b32_e32 v62, v121
	v_pk_fma_f32 v[38:39], v[120:121], v[54:55], v[60:61] neg_lo:[0,0,1] neg_hi:[0,0,1]
	v_pk_fma_f32 v[40:41], v[120:121], v[54:55], v[60:61] op_sel_hi:[0,1,1]
	v_pk_mul_f32 v[52:53], v[64:65], v[56:57] op_sel:[0,1] op_sel_hi:[0,0]
	v_mov_b32_e32 v51, v21
	v_pk_mul_f32 v[24:25], v[42:43], v[66:67]
	v_mov_b32_e32 v39, v41
	v_mov_b32_e32 v23, v117
	v_pk_fma_f32 v[20:21], v[22:23], v[56:57], v[52:53] neg_lo:[0,0,1] neg_hi:[0,0,1]
	v_pk_fma_f32 v[22:23], v[62:63], v[56:57], v[52:53] op_sel_hi:[0,1,1]
	v_pk_mul_f32 v[40:41], v[44:45], v[50:51]
	v_sub_f32_e32 v19, v24, v25
	v_pk_mul_f32 v[38:39], v[46:47], v[38:39]
	v_mov_b32_e32 v21, v23
	v_sub_f32_e32 v22, v40, v41
	v_add_f32_e32 v2, v2, v19
	v_sub_f32_e32 v23, v38, v39
	v_pk_mul_f32 v[20:21], v[48:49], v[20:21]
	v_add_f32_e32 v2, v2, v22
	v_sub_f32_e32 v19, v20, v21
	v_add_f32_e32 v2, v2, v23
	v_add_f32_e32 v2, v2, v19
	s_nop 0
	s_nop 0
	s_nop 0
	v_mov_b32_e32 v19, s12
	ds_read2_b64 v[42:45], v18 offset1:16
	ds_read2_b64 v[46:49], v18 offset0:32 offset1:48
	ds_read_b128 v[50:53], v19
	ds_read_b128 v[54:57], v19 offset:16
	s_add_i32 s12, s12, 32
	v_add_u32_e32 v18, 0x200, v18
	s_waitcnt vmcnt(23) lgkmcnt(1)
	v_pk_mul_f32 v[24:25], v[122:123], v[50:51] op_sel:[0,1] op_sel_hi:[0,0]
	s_waitcnt vmcnt(22)
	v_mov_b32_e32 v58, v127
	v_pk_mul_f32 v[20:21], v[122:123], v[52:53] op_sel:[1,1] op_sel_hi:[1,0]
	v_pk_fma_f32 v[66:67], v[126:127], v[50:51], v[24:25] neg_lo:[0,0,1] neg_hi:[0,0,1]
	v_pk_fma_f32 v[24:25], v[126:127], v[50:51], v[24:25] op_sel_hi:[0,1,1]
	s_waitcnt lgkmcnt(0)
	v_pk_mul_f32 v[60:61], v[124:125], v[54:55] op_sel:[0,1] op_sel_hi:[0,0]
	v_mov_b32_e32 v64, v125
	v_pk_fma_f32 v[50:51], v[58:59], v[52:53], v[20:21] neg_lo:[0,0,1] neg_hi:[0,0,1]
	v_pk_fma_f32 v[20:21], v[126:127], v[52:53], v[20:21] op_sel:[1,0,0]
	v_mov_b32_e32 v67, v25
	v_mov_b32_e32 v22, v129
	v_mov_b32_e32 v62, v129
	v_pk_fma_f32 v[38:39], v[128:129], v[54:55], v[60:61] neg_lo:[0,0,1] neg_hi:[0,0,1]
	v_pk_fma_f32 v[40:41], v[128:129], v[54:55], v[60:61] op_sel_hi:[0,1,1]
	v_pk_mul_f32 v[52:53], v[64:65], v[56:57] op_sel:[0,1] op_sel_hi:[0,0]
	v_mov_b32_e32 v51, v21
	v_pk_mul_f32 v[24:25], v[42:43], v[66:67]
	v_mov_b32_e32 v39, v41
	v_mov_b32_e32 v23, v125
	v_pk_fma_f32 v[20:21], v[22:23], v[56:57], v[52:53] neg_lo:[0,0,1] neg_hi:[0,0,1]
	v_pk_fma_f32 v[22:23], v[62:63], v[56:57], v[52:53] op_sel_hi:[0,1,1]
	v_pk_mul_f32 v[40:41], v[44:45], v[50:51]
	v_sub_f32_e32 v19, v24, v25
	v_pk_mul_f32 v[38:39], v[46:47], v[38:39]
	v_mov_b32_e32 v21, v23
	v_sub_f32_e32 v22, v40, v41
	v_add_f32_e32 v2, v2, v19
	v_sub_f32_e32 v23, v38, v39
	v_pk_mul_f32 v[20:21], v[48:49], v[20:21]
	v_add_f32_e32 v2, v2, v22
	v_sub_f32_e32 v19, v20, v21
	v_add_f32_e32 v2, v2, v23
	v_add_f32_e32 v2, v2, v19
	s_nop 0
	s_nop 0
	s_nop 0
	v_mov_b32_e32 v19, s12
	ds_read2_b64 v[42:45], v18 offset1:16
	ds_read2_b64 v[46:49], v18 offset0:32 offset1:48
	ds_read_b128 v[50:53], v19
	ds_read_b128 v[54:57], v19 offset:16
	s_add_i32 s12, s12, 32
	v_add_u32_e32 v18, 0x200, v18
	s_waitcnt vmcnt(21) lgkmcnt(1)
	v_pk_mul_f32 v[24:25], v[130:131], v[50:51] op_sel:[0,1] op_sel_hi:[0,0]
	s_waitcnt vmcnt(20)
	v_mov_b32_e32 v58, v135
	v_pk_mul_f32 v[20:21], v[130:131], v[52:53] op_sel:[1,1] op_sel_hi:[1,0]
	v_pk_fma_f32 v[66:67], v[134:135], v[50:51], v[24:25] neg_lo:[0,0,1] neg_hi:[0,0,1]
	v_pk_fma_f32 v[24:25], v[134:135], v[50:51], v[24:25] op_sel_hi:[0,1,1]
	s_waitcnt lgkmcnt(0)
	v_pk_mul_f32 v[60:61], v[132:133], v[54:55] op_sel:[0,1] op_sel_hi:[0,0]
	v_mov_b32_e32 v64, v133
	v_pk_fma_f32 v[50:51], v[58:59], v[52:53], v[20:21] neg_lo:[0,0,1] neg_hi:[0,0,1]
	v_pk_fma_f32 v[20:21], v[134:135], v[52:53], v[20:21] op_sel:[1,0,0]
	v_mov_b32_e32 v67, v25
	v_mov_b32_e32 v22, v137
	v_mov_b32_e32 v62, v137
	v_pk_fma_f32 v[38:39], v[136:137], v[54:55], v[60:61] neg_lo:[0,0,1] neg_hi:[0,0,1]
	v_pk_fma_f32 v[40:41], v[136:137], v[54:55], v[60:61] op_sel_hi:[0,1,1]
	v_pk_mul_f32 v[52:53], v[64:65], v[56:57] op_sel:[0,1] op_sel_hi:[0,0]
	v_mov_b32_e32 v51, v21
	v_pk_mul_f32 v[24:25], v[42:43], v[66:67]
	v_mov_b32_e32 v39, v41
	v_mov_b32_e32 v23, v133
	v_pk_fma_f32 v[20:21], v[22:23], v[56:57], v[52:53] neg_lo:[0,0,1] neg_hi:[0,0,1]
	v_pk_fma_f32 v[22:23], v[62:63], v[56:57], v[52:53] op_sel_hi:[0,1,1]
	v_pk_mul_f32 v[40:41], v[44:45], v[50:51]
	v_sub_f32_e32 v19, v24, v25
	v_pk_mul_f32 v[38:39], v[46:47], v[38:39]
	v_mov_b32_e32 v21, v23
	v_sub_f32_e32 v22, v40, v41
	v_add_f32_e32 v2, v2, v19
	v_sub_f32_e32 v23, v38, v39
	v_pk_mul_f32 v[20:21], v[48:49], v[20:21]
	v_add_f32_e32 v2, v2, v22
	v_sub_f32_e32 v19, v20, v21
	v_add_f32_e32 v2, v2, v23
	v_add_f32_e32 v2, v2, v19
	s_nop 0
	s_nop 0
	s_nop 0
	v_mov_b32_e32 v19, s12
	ds_read2_b64 v[42:45], v18 offset1:16
	ds_read2_b64 v[46:49], v18 offset0:32 offset1:48
	ds_read_b128 v[50:53], v19
	ds_read_b128 v[54:57], v19 offset:16
	s_add_i32 s12, s12, 32
	v_add_u32_e32 v18, 0x200, v18
	s_waitcnt vmcnt(19) lgkmcnt(1)
	v_pk_mul_f32 v[24:25], v[142:143], v[50:51] op_sel:[0,1] op_sel_hi:[0,0]
	s_waitcnt vmcnt(18)
	v_mov_b32_e32 v58, v147
	v_pk_mul_f32 v[20:21], v[142:143], v[52:53] op_sel:[1,1] op_sel_hi:[1,0]
	v_pk_fma_f32 v[66:67], v[146:147], v[50:51], v[24:25] neg_lo:[0,0,1] neg_hi:[0,0,1]
	v_pk_fma_f32 v[24:25], v[146:147], v[50:51], v[24:25] op_sel_hi:[0,1,1]
	s_waitcnt lgkmcnt(0)
	v_pk_mul_f32 v[60:61], v[144:145], v[54:55] op_sel:[0,1] op_sel_hi:[0,0]
	v_mov_b32_e32 v64, v145
	v_pk_fma_f32 v[50:51], v[58:59], v[52:53], v[20:21] neg_lo:[0,0,1] neg_hi:[0,0,1]
	v_pk_fma_f32 v[20:21], v[146:147], v[52:53], v[20:21] op_sel:[1,0,0]
	v_mov_b32_e32 v67, v25
	v_mov_b32_e32 v22, v149
	v_mov_b32_e32 v62, v149
	v_pk_fma_f32 v[38:39], v[148:149], v[54:55], v[60:61] neg_lo:[0,0,1] neg_hi:[0,0,1]
	v_pk_fma_f32 v[40:41], v[148:149], v[54:55], v[60:61] op_sel_hi:[0,1,1]
	v_pk_mul_f32 v[52:53], v[64:65], v[56:57] op_sel:[0,1] op_sel_hi:[0,0]
	v_mov_b32_e32 v51, v21
	v_pk_mul_f32 v[24:25], v[42:43], v[66:67]
	v_mov_b32_e32 v39, v41
	v_mov_b32_e32 v23, v145
	v_pk_fma_f32 v[20:21], v[22:23], v[56:57], v[52:53] neg_lo:[0,0,1] neg_hi:[0,0,1]
	v_pk_fma_f32 v[22:23], v[62:63], v[56:57], v[52:53] op_sel_hi:[0,1,1]
	v_pk_mul_f32 v[40:41], v[44:45], v[50:51]
	v_sub_f32_e32 v19, v24, v25
	v_pk_mul_f32 v[38:39], v[46:47], v[38:39]
	v_mov_b32_e32 v21, v23
	v_sub_f32_e32 v22, v40, v41
	v_add_f32_e32 v2, v2, v19
	v_sub_f32_e32 v23, v38, v39
	v_pk_mul_f32 v[20:21], v[48:49], v[20:21]
	v_add_f32_e32 v2, v2, v22
	v_sub_f32_e32 v19, v20, v21
	v_add_f32_e32 v2, v2, v23
	v_add_f32_e32 v2, v2, v19
	s_nop 0
	s_nop 0
	s_nop 0
	v_mov_b32_e32 v19, s12
	ds_read2_b64 v[42:45], v18 offset1:16
	ds_read2_b64 v[46:49], v18 offset0:32 offset1:48
	ds_read_b128 v[50:53], v19
	ds_read_b128 v[54:57], v19 offset:16
	s_add_i32 s12, s12, 32
	v_add_u32_e32 v18, 0x200, v18
	s_waitcnt vmcnt(17) lgkmcnt(1)
	v_pk_mul_f32 v[24:25], v[150:151], v[50:51] op_sel:[0,1] op_sel_hi:[0,0]
	s_waitcnt vmcnt(16)
	v_mov_b32_e32 v58, v155
	v_pk_mul_f32 v[20:21], v[150:151], v[52:53] op_sel:[1,1] op_sel_hi:[1,0]
	v_pk_fma_f32 v[66:67], v[154:155], v[50:51], v[24:25] neg_lo:[0,0,1] neg_hi:[0,0,1]
	v_pk_fma_f32 v[24:25], v[154:155], v[50:51], v[24:25] op_sel_hi:[0,1,1]
	s_waitcnt lgkmcnt(0)
	v_pk_mul_f32 v[60:61], v[152:153], v[54:55] op_sel:[0,1] op_sel_hi:[0,0]
	v_mov_b32_e32 v64, v153
	v_pk_fma_f32 v[50:51], v[58:59], v[52:53], v[20:21] neg_lo:[0,0,1] neg_hi:[0,0,1]
	v_pk_fma_f32 v[20:21], v[154:155], v[52:53], v[20:21] op_sel:[1,0,0]
	v_mov_b32_e32 v67, v25
	v_mov_b32_e32 v22, v157
	v_mov_b32_e32 v62, v157
	v_pk_fma_f32 v[38:39], v[156:157], v[54:55], v[60:61] neg_lo:[0,0,1] neg_hi:[0,0,1]
	v_pk_fma_f32 v[40:41], v[156:157], v[54:55], v[60:61] op_sel_hi:[0,1,1]
	v_pk_mul_f32 v[52:53], v[64:65], v[56:57] op_sel:[0,1] op_sel_hi:[0,0]
	v_mov_b32_e32 v51, v21
	v_pk_mul_f32 v[24:25], v[42:43], v[66:67]
	v_mov_b32_e32 v39, v41
	v_mov_b32_e32 v23, v153
	v_pk_fma_f32 v[20:21], v[22:23], v[56:57], v[52:53] neg_lo:[0,0,1] neg_hi:[0,0,1]
	v_pk_fma_f32 v[22:23], v[62:63], v[56:57], v[52:53] op_sel_hi:[0,1,1]
	v_pk_mul_f32 v[40:41], v[44:45], v[50:51]
	v_sub_f32_e32 v19, v24, v25
	v_pk_mul_f32 v[38:39], v[46:47], v[38:39]
	v_mov_b32_e32 v21, v23
	v_sub_f32_e32 v22, v40, v41
	v_add_f32_e32 v2, v2, v19
	v_sub_f32_e32 v23, v38, v39
	v_pk_mul_f32 v[20:21], v[48:49], v[20:21]
	v_add_f32_e32 v2, v2, v22
	v_sub_f32_e32 v19, v20, v21
	v_add_f32_e32 v2, v2, v23
	v_add_f32_e32 v2, v2, v19
	s_nop 0
	s_nop 0
	s_nop 0
	v_mov_b32_e32 v19, s12
	ds_read2_b64 v[42:45], v18 offset1:16
	ds_read2_b64 v[46:49], v18 offset0:32 offset1:48
	ds_read_b128 v[50:53], v19
	ds_read_b128 v[54:57], v19 offset:16
	s_add_i32 s12, s12, 32
	v_add_u32_e32 v18, 0x200, v18
	s_waitcnt vmcnt(15) lgkmcnt(1)
	v_pk_mul_f32 v[24:25], v[158:159], v[50:51] op_sel:[0,1] op_sel_hi:[0,0]
	s_waitcnt vmcnt(14)
	v_mov_b32_e32 v58, v163
	v_pk_mul_f32 v[20:21], v[158:159], v[52:53] op_sel:[1,1] op_sel_hi:[1,0]
	v_pk_fma_f32 v[66:67], v[162:163], v[50:51], v[24:25] neg_lo:[0,0,1] neg_hi:[0,0,1]
	v_pk_fma_f32 v[24:25], v[162:163], v[50:51], v[24:25] op_sel_hi:[0,1,1]
	s_waitcnt lgkmcnt(0)
	v_pk_mul_f32 v[60:61], v[160:161], v[54:55] op_sel:[0,1] op_sel_hi:[0,0]
	v_mov_b32_e32 v64, v161
	v_pk_fma_f32 v[50:51], v[58:59], v[52:53], v[20:21] neg_lo:[0,0,1] neg_hi:[0,0,1]
	v_pk_fma_f32 v[20:21], v[162:163], v[52:53], v[20:21] op_sel:[1,0,0]
	v_mov_b32_e32 v67, v25
	v_mov_b32_e32 v22, v165
	v_mov_b32_e32 v62, v165
	v_pk_fma_f32 v[38:39], v[164:165], v[54:55], v[60:61] neg_lo:[0,0,1] neg_hi:[0,0,1]
	v_pk_fma_f32 v[40:41], v[164:165], v[54:55], v[60:61] op_sel_hi:[0,1,1]
	v_pk_mul_f32 v[52:53], v[64:65], v[56:57] op_sel:[0,1] op_sel_hi:[0,0]
	v_mov_b32_e32 v51, v21
	v_pk_mul_f32 v[24:25], v[42:43], v[66:67]
	v_mov_b32_e32 v39, v41
	v_mov_b32_e32 v23, v161
	v_pk_fma_f32 v[20:21], v[22:23], v[56:57], v[52:53] neg_lo:[0,0,1] neg_hi:[0,0,1]
	v_pk_fma_f32 v[22:23], v[62:63], v[56:57], v[52:53] op_sel_hi:[0,1,1]
	v_pk_mul_f32 v[40:41], v[44:45], v[50:51]
	v_sub_f32_e32 v19, v24, v25
	v_pk_mul_f32 v[38:39], v[46:47], v[38:39]
	v_mov_b32_e32 v21, v23
	v_sub_f32_e32 v22, v40, v41
	v_add_f32_e32 v2, v2, v19
	v_sub_f32_e32 v23, v38, v39
	v_pk_mul_f32 v[20:21], v[48:49], v[20:21]
	v_add_f32_e32 v2, v2, v22
	v_sub_f32_e32 v19, v20, v21
	v_add_f32_e32 v2, v2, v23
	v_add_f32_e32 v2, v2, v19
	s_nop 0
	s_nop 0
	s_nop 0
	v_mov_b32_e32 v19, s12
	ds_read2_b64 v[42:45], v18 offset1:16
	ds_read2_b64 v[46:49], v18 offset0:32 offset1:48
	ds_read_b128 v[50:53], v19
	ds_read_b128 v[54:57], v19 offset:16
	s_add_i32 s12, s12, 32
	v_add_u32_e32 v18, 0x200, v18
	s_waitcnt vmcnt(13) lgkmcnt(1)
	v_pk_mul_f32 v[24:25], v[166:167], v[50:51] op_sel:[0,1] op_sel_hi:[0,0]
	s_waitcnt vmcnt(12)
	v_mov_b32_e32 v58, v171
	v_pk_mul_f32 v[20:21], v[166:167], v[52:53] op_sel:[1,1] op_sel_hi:[1,0]
	v_pk_fma_f32 v[66:67], v[170:171], v[50:51], v[24:25] neg_lo:[0,0,1] neg_hi:[0,0,1]
	v_pk_fma_f32 v[24:25], v[170:171], v[50:51], v[24:25] op_sel_hi:[0,1,1]
	s_waitcnt lgkmcnt(0)
	v_pk_mul_f32 v[60:61], v[168:169], v[54:55] op_sel:[0,1] op_sel_hi:[0,0]
	v_mov_b32_e32 v64, v169
	v_pk_fma_f32 v[50:51], v[58:59], v[52:53], v[20:21] neg_lo:[0,0,1] neg_hi:[0,0,1]
	v_pk_fma_f32 v[20:21], v[170:171], v[52:53], v[20:21] op_sel:[1,0,0]
	v_mov_b32_e32 v67, v25
	v_mov_b32_e32 v22, v173
	v_mov_b32_e32 v62, v173
	v_pk_fma_f32 v[38:39], v[172:173], v[54:55], v[60:61] neg_lo:[0,0,1] neg_hi:[0,0,1]
	v_pk_fma_f32 v[40:41], v[172:173], v[54:55], v[60:61] op_sel_hi:[0,1,1]
	v_pk_mul_f32 v[52:53], v[64:65], v[56:57] op_sel:[0,1] op_sel_hi:[0,0]
	v_mov_b32_e32 v51, v21
	v_pk_mul_f32 v[24:25], v[42:43], v[66:67]
	v_mov_b32_e32 v39, v41
	v_mov_b32_e32 v23, v169
	v_pk_fma_f32 v[20:21], v[22:23], v[56:57], v[52:53] neg_lo:[0,0,1] neg_hi:[0,0,1]
	v_pk_fma_f32 v[22:23], v[62:63], v[56:57], v[52:53] op_sel_hi:[0,1,1]
	v_pk_mul_f32 v[40:41], v[44:45], v[50:51]
	v_sub_f32_e32 v19, v24, v25
	v_pk_mul_f32 v[38:39], v[46:47], v[38:39]
	v_mov_b32_e32 v21, v23
	v_sub_f32_e32 v22, v40, v41
	v_add_f32_e32 v2, v2, v19
	v_sub_f32_e32 v23, v38, v39
	v_pk_mul_f32 v[20:21], v[48:49], v[20:21]
	v_add_f32_e32 v2, v2, v22
	v_sub_f32_e32 v19, v20, v21
	v_add_f32_e32 v2, v2, v23
	v_add_f32_e32 v2, v2, v19
	s_nop 0
	s_nop 0
	s_nop 0
	v_mov_b32_e32 v19, s12
	ds_read2_b64 v[42:45], v18 offset1:16
	ds_read2_b64 v[46:49], v18 offset0:32 offset1:48
	ds_read_b128 v[50:53], v19
	ds_read_b128 v[54:57], v19 offset:16
	s_add_i32 s12, s12, 32
	v_add_u32_e32 v18, 0x200, v18
	s_waitcnt vmcnt(11) lgkmcnt(1)
	v_pk_mul_f32 v[24:25], v[174:175], v[50:51] op_sel:[0,1] op_sel_hi:[0,0]
	s_waitcnt vmcnt(10)
	v_mov_b32_e32 v58, v183
	v_pk_mul_f32 v[20:21], v[174:175], v[52:53] op_sel:[1,1] op_sel_hi:[1,0]
	v_pk_fma_f32 v[66:67], v[182:183], v[50:51], v[24:25] neg_lo:[0,0,1] neg_hi:[0,0,1]
	v_pk_fma_f32 v[24:25], v[182:183], v[50:51], v[24:25] op_sel_hi:[0,1,1]
	s_waitcnt lgkmcnt(0)
	v_pk_mul_f32 v[60:61], v[176:177], v[54:55] op_sel:[0,1] op_sel_hi:[0,0]
	v_mov_b32_e32 v64, v177
	v_pk_fma_f32 v[50:51], v[58:59], v[52:53], v[20:21] neg_lo:[0,0,1] neg_hi:[0,0,1]
	v_pk_fma_f32 v[20:21], v[182:183], v[52:53], v[20:21] op_sel:[1,0,0]
	v_mov_b32_e32 v67, v25
	v_mov_b32_e32 v22, v185
	v_mov_b32_e32 v62, v185
	v_pk_fma_f32 v[38:39], v[184:185], v[54:55], v[60:61] neg_lo:[0,0,1] neg_hi:[0,0,1]
	v_pk_fma_f32 v[40:41], v[184:185], v[54:55], v[60:61] op_sel_hi:[0,1,1]
	v_pk_mul_f32 v[52:53], v[64:65], v[56:57] op_sel:[0,1] op_sel_hi:[0,0]
	v_mov_b32_e32 v51, v21
	v_pk_mul_f32 v[24:25], v[42:43], v[66:67]
	v_mov_b32_e32 v39, v41
	v_mov_b32_e32 v23, v177
	v_pk_fma_f32 v[20:21], v[22:23], v[56:57], v[52:53] neg_lo:[0,0,1] neg_hi:[0,0,1]
	v_pk_fma_f32 v[22:23], v[62:63], v[56:57], v[52:53] op_sel_hi:[0,1,1]
	v_pk_mul_f32 v[40:41], v[44:45], v[50:51]
	v_sub_f32_e32 v19, v24, v25
	v_pk_mul_f32 v[38:39], v[46:47], v[38:39]
	v_mov_b32_e32 v21, v23
	v_sub_f32_e32 v22, v40, v41
	v_add_f32_e32 v2, v2, v19
	v_sub_f32_e32 v23, v38, v39
	v_pk_mul_f32 v[20:21], v[48:49], v[20:21]
	v_add_f32_e32 v2, v2, v22
	v_sub_f32_e32 v19, v20, v21
	v_add_f32_e32 v2, v2, v23
	v_add_f32_e32 v2, v2, v19
	s_nop 0
	s_nop 0
	s_nop 0
	v_mov_b32_e32 v19, s12
	ds_read2_b64 v[42:45], v18 offset1:16
	ds_read2_b64 v[46:49], v18 offset0:32 offset1:48
	ds_read_b128 v[50:53], v19
	ds_read_b128 v[54:57], v19 offset:16
	s_add_i32 s12, s12, 32
	v_add_u32_e32 v18, 0x200, v18
	s_waitcnt vmcnt(9) lgkmcnt(1)
	v_pk_mul_f32 v[24:25], v[186:187], v[50:51] op_sel:[0,1] op_sel_hi:[0,0]
	s_waitcnt vmcnt(8)
	v_mov_b32_e32 v58, v191
	v_pk_mul_f32 v[20:21], v[186:187], v[52:53] op_sel:[1,1] op_sel_hi:[1,0]
	v_pk_fma_f32 v[66:67], v[190:191], v[50:51], v[24:25] neg_lo:[0,0,1] neg_hi:[0,0,1]
	v_pk_fma_f32 v[24:25], v[190:191], v[50:51], v[24:25] op_sel_hi:[0,1,1]
	s_waitcnt lgkmcnt(0)
	v_pk_mul_f32 v[60:61], v[188:189], v[54:55] op_sel:[0,1] op_sel_hi:[0,0]
	v_mov_b32_e32 v64, v189
	v_pk_fma_f32 v[50:51], v[58:59], v[52:53], v[20:21] neg_lo:[0,0,1] neg_hi:[0,0,1]
	v_pk_fma_f32 v[20:21], v[190:191], v[52:53], v[20:21] op_sel:[1,0,0]
	v_mov_b32_e32 v67, v25
	v_mov_b32_e32 v22, v193
	v_mov_b32_e32 v62, v193
	v_pk_fma_f32 v[38:39], v[192:193], v[54:55], v[60:61] neg_lo:[0,0,1] neg_hi:[0,0,1]
	v_pk_fma_f32 v[40:41], v[192:193], v[54:55], v[60:61] op_sel_hi:[0,1,1]
	v_pk_mul_f32 v[52:53], v[64:65], v[56:57] op_sel:[0,1] op_sel_hi:[0,0]
	v_mov_b32_e32 v51, v21
	v_pk_mul_f32 v[24:25], v[42:43], v[66:67]
	v_mov_b32_e32 v39, v41
	v_mov_b32_e32 v23, v189
	v_pk_fma_f32 v[20:21], v[22:23], v[56:57], v[52:53] neg_lo:[0,0,1] neg_hi:[0,0,1]
	v_pk_fma_f32 v[22:23], v[62:63], v[56:57], v[52:53] op_sel_hi:[0,1,1]
	v_pk_mul_f32 v[40:41], v[44:45], v[50:51]
	v_sub_f32_e32 v19, v24, v25
	v_pk_mul_f32 v[38:39], v[46:47], v[38:39]
	v_mov_b32_e32 v21, v23
	v_sub_f32_e32 v22, v40, v41
	v_add_f32_e32 v2, v2, v19
	v_sub_f32_e32 v23, v38, v39
	v_pk_mul_f32 v[20:21], v[48:49], v[20:21]
	v_add_f32_e32 v2, v2, v22
	v_sub_f32_e32 v19, v20, v21
	v_add_f32_e32 v2, v2, v23
	v_add_f32_e32 v2, v2, v19
	s_nop 0
	s_nop 0
	s_nop 0
	v_mov_b32_e32 v19, s12
	ds_read2_b64 v[42:45], v18 offset1:16
	ds_read2_b64 v[46:49], v18 offset0:32 offset1:48
	ds_read_b128 v[50:53], v19
	ds_read_b128 v[54:57], v19 offset:16
	s_add_i32 s12, s12, 32
	v_add_u32_e32 v18, 0x200, v18
	s_waitcnt vmcnt(7) lgkmcnt(1)
	v_pk_mul_f32 v[24:25], v[194:195], v[50:51] op_sel:[0,1] op_sel_hi:[0,0]
	s_waitcnt vmcnt(6)
	v_mov_b32_e32 v58, v199
	v_pk_mul_f32 v[20:21], v[194:195], v[52:53] op_sel:[1,1] op_sel_hi:[1,0]
	v_pk_fma_f32 v[66:67], v[198:199], v[50:51], v[24:25] neg_lo:[0,0,1] neg_hi:[0,0,1]
	v_pk_fma_f32 v[24:25], v[198:199], v[50:51], v[24:25] op_sel_hi:[0,1,1]
	s_waitcnt lgkmcnt(0)
	v_pk_mul_f32 v[60:61], v[196:197], v[54:55] op_sel:[0,1] op_sel_hi:[0,0]
	v_mov_b32_e32 v64, v197
	v_pk_fma_f32 v[50:51], v[58:59], v[52:53], v[20:21] neg_lo:[0,0,1] neg_hi:[0,0,1]
	v_pk_fma_f32 v[20:21], v[198:199], v[52:53], v[20:21] op_sel:[1,0,0]
	v_mov_b32_e32 v67, v25
	v_mov_b32_e32 v22, v201
	v_mov_b32_e32 v62, v201
	v_pk_fma_f32 v[38:39], v[200:201], v[54:55], v[60:61] neg_lo:[0,0,1] neg_hi:[0,0,1]
	v_pk_fma_f32 v[40:41], v[200:201], v[54:55], v[60:61] op_sel_hi:[0,1,1]
	v_pk_mul_f32 v[52:53], v[64:65], v[56:57] op_sel:[0,1] op_sel_hi:[0,0]
	v_mov_b32_e32 v51, v21
	v_pk_mul_f32 v[24:25], v[42:43], v[66:67]
	v_mov_b32_e32 v39, v41
	v_mov_b32_e32 v23, v197
	v_pk_fma_f32 v[20:21], v[22:23], v[56:57], v[52:53] neg_lo:[0,0,1] neg_hi:[0,0,1]
	v_pk_fma_f32 v[22:23], v[62:63], v[56:57], v[52:53] op_sel_hi:[0,1,1]
	v_pk_mul_f32 v[40:41], v[44:45], v[50:51]
	v_sub_f32_e32 v19, v24, v25
	v_pk_mul_f32 v[38:39], v[46:47], v[38:39]
	v_mov_b32_e32 v21, v23
	v_sub_f32_e32 v22, v40, v41
	v_add_f32_e32 v2, v2, v19
	v_sub_f32_e32 v23, v38, v39
	v_pk_mul_f32 v[20:21], v[48:49], v[20:21]
	v_add_f32_e32 v2, v2, v22
	v_sub_f32_e32 v19, v20, v21
	v_add_f32_e32 v2, v2, v23
	v_add_f32_e32 v2, v2, v19
	s_nop 0
	s_nop 0
	s_nop 0
	v_mov_b32_e32 v19, s12
	ds_read2_b64 v[42:45], v18 offset1:16
	ds_read2_b64 v[46:49], v18 offset0:32 offset1:48
	ds_read_b128 v[50:53], v19
	ds_read_b128 v[54:57], v19 offset:16
	s_add_i32 s12, s12, 32
	v_add_u32_e32 v18, 0x200, v18
	s_waitcnt vmcnt(5) lgkmcnt(1)
	v_pk_mul_f32 v[24:25], v[202:203], v[50:51] op_sel:[0,1] op_sel_hi:[0,0]
	s_waitcnt vmcnt(4)
	v_mov_b32_e32 v58, v207
	v_pk_mul_f32 v[20:21], v[202:203], v[52:53] op_sel:[1,1] op_sel_hi:[1,0]
	v_pk_fma_f32 v[66:67], v[206:207], v[50:51], v[24:25] neg_lo:[0,0,1] neg_hi:[0,0,1]
	v_pk_fma_f32 v[24:25], v[206:207], v[50:51], v[24:25] op_sel_hi:[0,1,1]
	s_waitcnt lgkmcnt(0)
	v_pk_mul_f32 v[60:61], v[204:205], v[54:55] op_sel:[0,1] op_sel_hi:[0,0]
	v_mov_b32_e32 v64, v205
	v_pk_fma_f32 v[50:51], v[58:59], v[52:53], v[20:21] neg_lo:[0,0,1] neg_hi:[0,0,1]
	v_pk_fma_f32 v[20:21], v[206:207], v[52:53], v[20:21] op_sel:[1,0,0]
	v_mov_b32_e32 v67, v25
	v_mov_b32_e32 v22, v209
	v_mov_b32_e32 v62, v209
	v_pk_fma_f32 v[38:39], v[208:209], v[54:55], v[60:61] neg_lo:[0,0,1] neg_hi:[0,0,1]
	v_pk_fma_f32 v[40:41], v[208:209], v[54:55], v[60:61] op_sel_hi:[0,1,1]
	v_pk_mul_f32 v[52:53], v[64:65], v[56:57] op_sel:[0,1] op_sel_hi:[0,0]
	v_mov_b32_e32 v51, v21
	v_pk_mul_f32 v[24:25], v[42:43], v[66:67]
	v_mov_b32_e32 v39, v41
	v_mov_b32_e32 v23, v205
	v_pk_fma_f32 v[20:21], v[22:23], v[56:57], v[52:53] neg_lo:[0,0,1] neg_hi:[0,0,1]
	v_pk_fma_f32 v[22:23], v[62:63], v[56:57], v[52:53] op_sel_hi:[0,1,1]
	v_pk_mul_f32 v[40:41], v[44:45], v[50:51]
	v_sub_f32_e32 v19, v24, v25
	v_pk_mul_f32 v[38:39], v[46:47], v[38:39]
	v_mov_b32_e32 v21, v23
	v_sub_f32_e32 v22, v40, v41
	v_add_f32_e32 v2, v2, v19
	v_sub_f32_e32 v23, v38, v39
	v_pk_mul_f32 v[20:21], v[48:49], v[20:21]
	v_add_f32_e32 v2, v2, v22
	v_sub_f32_e32 v19, v20, v21
	v_add_f32_e32 v2, v2, v23
	v_add_f32_e32 v2, v2, v19
	s_nop 0
	s_nop 0
	s_nop 0
	v_mov_b32_e32 v19, s12
	ds_read2_b64 v[42:45], v18 offset1:16
	ds_read2_b64 v[46:49], v18 offset0:32 offset1:48
	ds_read_b128 v[50:53], v19
	ds_read_b128 v[54:57], v19 offset:16
	s_add_i32 s12, s12, 32
	v_add_u32_e32 v18, 0x200, v18
	s_waitcnt vmcnt(3) lgkmcnt(1)
	v_pk_mul_f32 v[24:25], v[210:211], v[50:51] op_sel:[0,1] op_sel_hi:[0,0]
	s_waitcnt vmcnt(2)
	v_mov_b32_e32 v58, v215
	v_pk_mul_f32 v[20:21], v[210:211], v[52:53] op_sel:[1,1] op_sel_hi:[1,0]
	v_pk_fma_f32 v[66:67], v[214:215], v[50:51], v[24:25] neg_lo:[0,0,1] neg_hi:[0,0,1]
	v_pk_fma_f32 v[24:25], v[214:215], v[50:51], v[24:25] op_sel_hi:[0,1,1]
	s_waitcnt lgkmcnt(0)
	v_pk_mul_f32 v[60:61], v[212:213], v[54:55] op_sel:[0,1] op_sel_hi:[0,0]
	v_mov_b32_e32 v64, v213
	v_pk_fma_f32 v[50:51], v[58:59], v[52:53], v[20:21] neg_lo:[0,0,1] neg_hi:[0,0,1]
	v_pk_fma_f32 v[20:21], v[214:215], v[52:53], v[20:21] op_sel:[1,0,0]
	v_mov_b32_e32 v67, v25
	v_mov_b32_e32 v22, v217
	v_mov_b32_e32 v62, v217
	v_pk_fma_f32 v[38:39], v[216:217], v[54:55], v[60:61] neg_lo:[0,0,1] neg_hi:[0,0,1]
	v_pk_fma_f32 v[40:41], v[216:217], v[54:55], v[60:61] op_sel_hi:[0,1,1]
	v_pk_mul_f32 v[52:53], v[64:65], v[56:57] op_sel:[0,1] op_sel_hi:[0,0]
	v_mov_b32_e32 v51, v21
	v_pk_mul_f32 v[24:25], v[42:43], v[66:67]
	v_mov_b32_e32 v39, v41
	v_mov_b32_e32 v23, v213
	v_pk_fma_f32 v[20:21], v[22:23], v[56:57], v[52:53] neg_lo:[0,0,1] neg_hi:[0,0,1]
	v_pk_fma_f32 v[22:23], v[62:63], v[56:57], v[52:53] op_sel_hi:[0,1,1]
	v_pk_mul_f32 v[40:41], v[44:45], v[50:51]
	v_sub_f32_e32 v19, v24, v25
	v_pk_mul_f32 v[38:39], v[46:47], v[38:39]
	v_mov_b32_e32 v21, v23
	v_sub_f32_e32 v22, v40, v41
	v_add_f32_e32 v2, v2, v19
	v_sub_f32_e32 v23, v38, v39
	v_pk_mul_f32 v[20:21], v[48:49], v[20:21]
	v_add_f32_e32 v2, v2, v22
	v_sub_f32_e32 v19, v20, v21
	v_add_f32_e32 v2, v2, v23
	v_add_f32_e32 v2, v2, v19
	s_nop 0
	s_nop 0
	s_nop 0
	v_mov_b32_e32 v19, s12
	ds_read2_b64 v[42:45], v18 offset1:16
	ds_read2_b64 v[46:49], v18 offset0:32 offset1:48
	ds_read_b128 v[50:53], v19
	ds_read_b128 v[54:57], v19 offset:16
	s_add_i32 s12, s12, 32
	v_add_u32_e32 v18, 0x200, v18
	s_waitcnt vmcnt(1) lgkmcnt(1)
	v_pk_mul_f32 v[24:25], v[218:219], v[50:51] op_sel:[0,1] op_sel_hi:[0,0]
	s_waitcnt vmcnt(0)
	v_mov_b32_e32 v58, v223
	v_pk_mul_f32 v[20:21], v[218:219], v[52:53] op_sel:[1,1] op_sel_hi:[1,0]
	v_pk_fma_f32 v[66:67], v[222:223], v[50:51], v[24:25] neg_lo:[0,0,1] neg_hi:[0,0,1]
	v_pk_fma_f32 v[24:25], v[222:223], v[50:51], v[24:25] op_sel_hi:[0,1,1]
	s_waitcnt lgkmcnt(0)
	v_pk_mul_f32 v[60:61], v[220:221], v[54:55] op_sel:[0,1] op_sel_hi:[0,0]
	v_mov_b32_e32 v64, v221
	v_pk_fma_f32 v[50:51], v[58:59], v[52:53], v[20:21] neg_lo:[0,0,1] neg_hi:[0,0,1]
	v_pk_fma_f32 v[20:21], v[222:223], v[52:53], v[20:21] op_sel:[1,0,0]
	v_mov_b32_e32 v67, v25
	v_mov_b32_e32 v22, v225
	v_mov_b32_e32 v62, v225
	v_pk_fma_f32 v[38:39], v[224:225], v[54:55], v[60:61] neg_lo:[0,0,1] neg_hi:[0,0,1]
	v_pk_fma_f32 v[40:41], v[224:225], v[54:55], v[60:61] op_sel_hi:[0,1,1]
	v_pk_mul_f32 v[52:53], v[64:65], v[56:57] op_sel:[0,1] op_sel_hi:[0,0]
	v_mov_b32_e32 v51, v21
	v_pk_mul_f32 v[24:25], v[42:43], v[66:67]
	v_mov_b32_e32 v39, v41
	v_mov_b32_e32 v23, v221
	v_pk_fma_f32 v[20:21], v[22:23], v[56:57], v[52:53] neg_lo:[0,0,1] neg_hi:[0,0,1]
	v_pk_fma_f32 v[22:23], v[62:63], v[56:57], v[52:53] op_sel_hi:[0,1,1]
	v_pk_mul_f32 v[40:41], v[44:45], v[50:51]
	v_sub_f32_e32 v19, v24, v25
	v_pk_mul_f32 v[38:39], v[46:47], v[38:39]
	v_mov_b32_e32 v21, v23
	v_sub_f32_e32 v22, v40, v41
	v_add_f32_e32 v2, v2, v19
	v_sub_f32_e32 v23, v38, v39
	v_pk_mul_f32 v[20:21], v[48:49], v[20:21]
	v_add_f32_e32 v2, v2, v22
	v_sub_f32_e32 v19, v20, v21
	v_add_f32_e32 v2, v2, v23
	v_add_f32_e32 v2, v2, v19
	s_and_b64 s[12:13], s[6:7], s[26:27]
	s_and_saveexec_b64 s[10:11], s[12:13]
	s_cbranch_execz .LBB0_124
	v_lshl_or_b32 v14, s24, 4, v27
	v_readlane_b32 s72, v244, 13
	v_ashrrev_i32_e32 v15, 31, v14
	v_readlane_b32 s74, v244, 15
	v_readlane_b32 s75, v244, 16
	v_readlane_b32 s73, v244, 14
	v_readlane_b32 s76, v244, 17
	v_lshl_add_u64 v[14:15], v[14:15], 2, s[74:75]
	global_load_dword v14, v[14:15], off
	v_readlane_b32 s77, v244, 18
	v_readlane_b32 s78, v244, 19
	v_readlane_b32 s79, v244, 20
	v_readlane_b32 s80, v244, 21
	v_readlane_b32 s81, v244, 22
	v_readlane_b32 s82, v244, 23
	v_readlane_b32 s83, v244, 24
	v_readlane_b32 s84, v244, 25
	v_readlane_b32 s85, v244, 26
	v_readlane_b32 s86, v244, 27
	v_readlane_b32 s87, v244, 28
	s_waitcnt vmcnt(0)
	v_add_f32_e32 v2, v2, v14
	s_branch .LBB0_124
